# v039
# speedup vs baseline: 1.0052x; 1.0052x over previous
.LBB0_290:
	s_or_b64 exec, exec, s[8:9]
	s_lshl_b32 s80, s2, 9
	s_lshl_b64 s[2:3], s[80:81], 2
	v_readlane_b32 s5, v254, 43
	s_add_u32 s42, s5, s2
	v_readlane_b32 s2, v254, 44
	s_addc_u32 s43, s2, s3
	s_getreg_b32 s20, hwreg(HW_REG_XCC_ID, 0, 4)
	v_sub_f32_e32 v200, 1.0, v0
	s_mov_b32 s101, -1
	s_branch .LBB0_292
.Lmy_pop4:
	s_cmp_eq_u32 s101, 0x100
	s_cbranch_scc0 .LBB0_291
	s_mov_b64 s[8:9], exec
	s_mov_b64 exec, 1
	s_mov_b32 s2, 0
	s_mov_b64 s[10:11], 0
	s_branch .Lmy_p295

.Lmy_p297:
	s_or_b64 exec, exec, s[10:11]
	v_mov_b32_e32 v2, s51
	ds_write_b32 v2, v0
	s_mov_b64 exec, s[8:9]

.LBB0_292:
	s_cmp_lt_i32 s101, 0
	s_cbranch_scc0 .Lmy_skip_pop
	s_mov_b64 s[8:9], exec
	v_readlane_b32 s2, v253, 29
	v_readlane_b32 s3, v253, 30
	s_and_b64 s[2:3], s[8:9], s[2:3]
	s_mov_b64 exec, s[2:3]
	s_cbranch_execz .LBB0_298
	s_mov_b32 s2, 0
	s_mov_b64 s[10:11], 0
	s_branch .LBB0_295

.Lmy_skip_pop:
	v_mov_b32_e32 v0, s51
	s_waitcnt lgkmcnt(0)
	s_barrier
	ds_read_b32 v0, v0
	s_waitcnt lgkmcnt(0)
	v_cmp_gt_i32_e32 vcc, 0, v0
	v_readfirstlane_b32 s2, v0
	s_cbranch_vccnz .LBB0_340
	s_mul_hi_u32 s3, s2, 0xaaaaaaab
	s_lshr_b32 s3, s3, 8
	s_mul_i32 s5, s3, 0x180
	s_sub_i32 s5, s2, s5
	s_lshr_b32 s7, s5, 2
	s_and_b32 s7, s7, 0x78
	s_sub_i32 s8, s7, s3
	s_and_b32 s2, s5, 32
	s_add_i32 s8, s8, 7
	s_add_i32 s7, s7, s3
	s_cmp_eq_u32 s2, 0
	s_cselect_b32 s3, s7, s8
	s_mul_hi_i32 s7, s3, 0x2aaaaaab
	s_lshr_b32 s8, s7, 31
	s_mul_hi_i32 s21, s3, 0xd5555555
	s_add_i32 s7, s7, s8
	s_lshr_b32 s2, s21, 31
	s_mul_i32 s7, s7, 6
	s_add_i32 s21, s21, s2
	s_sub_i32 s3, s3, s7
	s_add_i32 s2, s21, 15
	s_and_b32 s5, s5, 31
	s_lshl_b32 s7, s3, 5
	s_cmp_lt_i32 s3, 4
	s_cselect_b32 s7, s7, 0
	s_lshl_b32 s8, s2, 4
	s_add_i32 s8, s8, 0
	s_add_i32 s8, s8, 0x20000
	v_mov_b32_e32 v0, s8
	s_max_i32 s3, s3, 3
	s_waitcnt vmcnt(0)
	ds_read_b96 v[2:4], v0
	s_or_b32 s22, s5, s7
	s_add_i32 s18, s3, -3
	s_cmp_eq_u32 s18, 1
	s_movk_i32 s3, 0x5000
	v_readfirstlane_b32 s9, v195
	s_cselect_b32 s25, 0x4000, s3
	s_bfe_u32 s5, s9, 0x20006
	s_lshl_b32 s10, s22, 7
	s_lshl_b32 s11, s5, 5
	s_lshr_b32 s3, s9, 6
	s_lshr_b32 s7, s9, 8
	s_or_b32 s23, s11, s10
	s_mul_i32 s12, s2, 0x600000
	s_waitcnt lgkmcnt(0)
	v_readfirstlane_b32 s8, v2
	s_mul_hi_i32 s11, s2, 0x600000
	s_add_u32 s16, s63, s12
	s_addc_u32 s17, s4, s11
	s_sub_i32 s11, s10, s8
	s_or_b32 s24, s10, 0x7f
	s_ashr_i32 s11, s11, 6
	s_add_i32 s8, s8, s24
	s_lshl_b32 s80, s7, 7
	s_add_i32 s33, s21, 16
	s_max_i32 s11, s11, 0
	s_ashr_i32 s12, s8, 6
	s_cmpk_lt_u32 s9, 0x100
	s_cselect_b64 s[8:9], -1, 0
	s_and_b64 s[14:15], s[8:9], exec
	v_readfirstlane_b32 s13, v3
	v_readfirstlane_b32 s19, v4
	s_cselect_b32 s14, 16, 32
	v_mov_b32_e32 v0, v195
	v_mov_b32_e32 v181, v194
	s_cselect_b32 s13, s13, s19
	s_add_i32 s15, s14, s2
	s_lshl_b32 s19, s5, 11
	s_cmp_eq_u32 s18, 0
	v_and_b32_e32 v0, 31, v181
	s_cselect_b32 s14, 0, s25
	v_or_b32_e32 v10, s23, v0
	v_add_u32_e32 v164, s14, v10
	v_ashrrev_i32_e32 v165, 31, v164
	v_ashrrev_i32_e32 v186, 5, v181
	v_lshlrev_b64 v[2:3], 8, v[164:165]
	v_lshl_add_u64 v[2:3], s[16:17], 0, v[2:3]
	v_lshlrev_b32_e32 v166, 3, v186
	v_lshl_add_u64 v[2:3], v[2:3], 0, s[80:81]
	v_ashrrev_i32_e32 v167, 31, v166
	v_lshl_add_u64 v[2:3], v[166:167], 1, v[2:3]
	global_load_dwordx4 v[144:147], v[2:3], off
	global_load_dwordx4 v[148:151], v[2:3], off offset:32
	global_load_dwordx4 v[152:155], v[2:3], off offset:64
	global_load_dwordx4 v[156:159], v[2:3], off offset:96
	v_lshlrev_b32_e32 v3, 2, v181
	v_lshl_add_u32 v2, s7, 3, v186
	v_and_b32_e32 v3, 12, v3
	v_bfe_u32 v4, v181, 2, 2
	v_lshlrev_b32_e32 v0, 8, v0
	v_bitop3_b32 v5, v3, v2, v4 bitop3:0x36
	v_lshl_add_u32 v182, v5, 4, v0
	v_add_u32_e32 v5, 2, v2
	v_bitop3_b32 v5, v3, v5, v4 bitop3:0x36
	v_lshl_add_u32 v183, v5, 4, v0
	v_add_u32_e32 v5, 4, v2
	v_add_u32_e32 v2, 6, v2
	v_bitop3_b32 v5, v3, v5, v4 bitop3:0x36
	v_bitop3_b32 v2, v3, v2, v4 bitop3:0x36
	v_lshl_add_u32 v184, v5, 4, v0
	v_lshl_add_u32 v185, v2, 4, v0
	v_ashrrev_i32_e32 v0, 4, v181
	v_lshlrev_b32_e32 v3, 1, v0
	v_and_b32_e32 v7, 12, v181
	v_lshlrev_b32_e32 v11, 2, v186
	v_and_b32_e32 v3, 2, v3
	v_bfe_u32 v5, v181, 1, 1
	v_lshlrev_b32_e32 v8, 3, v181
	v_and_or_b32 v9, v186, 3, v7
	v_or_b32_e32 v6, v3, v5
	v_and_b32_e32 v12, 8, v8
	v_or_b32_e32 v8, v11, v4
	v_bitop3_b32 v3, v3, v9, v5 bitop3:0x36
	v_lshlrev_b32_e32 v8, 8, v8
	v_lshlrev_b32_e32 v3, 4, v3
	v_or3_b32 v187, v3, v8, v12
	v_add_u32_e32 v3, 8, v11
	v_or_b32_e32 v4, v3, v4
	v_bfe_u32 v3, v3, 2, 2
	v_lshlrev_b32_e32 v13, 8, v4
	v_bitop3_b32 v4, v3, v6, v7 bitop3:0x36
	v_lshlrev_b32_e32 v4, 4, v4
	v_or3_b32 v188, v4, v13, v12
	v_or_b32_e32 v4, 4, v6
	v_bitop3_b32 v4, v3, v4, v7 bitop3:0x36
	v_bitop3_b32 v5, v6, v9, 4 bitop3:0x36
	v_lshlrev_b32_e32 v4, 4, v4
	v_lshlrev_b32_e32 v5, 4, v5
	v_or3_b32 v190, v4, v13, v12
	v_or_b32_e32 v4, 8, v6
	v_or3_b32 v189, v5, v8, v12
	v_bitop3_b32 v5, v6, v9, 8 bitop3:0x36
	v_bitop3_b32 v4, v3, v4, v7 bitop3:0x36
	v_lshlrev_b32_e32 v5, 4, v5
	v_lshlrev_b32_e32 v4, 4, v4
	v_or3_b32 v191, v5, v8, v12
	v_or3_b32 v192, v4, v13, v12
	v_or_b32_e32 v4, 12, v6
	v_bitop3_b32 v5, v6, v9, 12 bitop3:0x36
	v_cvt_f32_i32_e32 v6, s33
	v_and_b32_e32 v2, 15, v181
	v_bitop3_b32 v14, v3, v4, v7 bitop3:0x36
	v_lshlrev_b32_e32 v5, 4, v5
	v_mul_f32_e32 v3, -0.5, v6
	v_exp_f32_e32 v15, v3
	v_lshl_add_u32 v3, v0, 7, s19
	v_lshlrev_b32_e32 v0, 5, v0
	v_lshlrev_b32_e32 v2, 3, v2
	v_or3_b32 v193, v5, v8, v12
	v_xor_b32_e32 v5, v0, v2
	v_xor_b32_e32 v2, 8, v5
	s_movk_i32 s17, 0x200
	v_add3_u32 v2, v3, v2, s17
	v_xor_b32_e32 v4, 16, v5
	s_movk_i32 s17, 0x400
	v_add_u32_e32 v0, v3, v5
	v_add3_u32 v4, v3, v4, s17
	v_xor_b32_e32 v5, 24, v5
	s_movk_i32 s17, 0x600
	v_add3_u32 v6, v3, v5, s17
	s_mul_hi_i32 s16, s15, 0x600000
	s_mul_i32 s15, s15, 0x600000
	s_waitcnt vmcnt(2)
	v_and_b32_e32 v7, 0xffff0000, v148
	v_and_b32_e32 v5, 0xffff0000, v144
	v_lshlrev_b32_e32 v3, 16, v144
	v_mul_f32_e32 v5, v5, v5
	v_fmac_f32_e32 v5, v3, v3
	v_lshlrev_b32_e32 v3, 16, v145
	v_fmac_f32_e32 v5, v3, v3
	v_and_b32_e32 v3, 0xffff0000, v145
	v_fmac_f32_e32 v5, v3, v3
	v_lshlrev_b32_e32 v3, 16, v146
	v_fmac_f32_e32 v5, v3, v3
	v_and_b32_e32 v3, 0xffff0000, v146
	v_fmac_f32_e32 v5, v3, v3
	v_lshlrev_b32_e32 v3, 16, v147
	v_fmac_f32_e32 v5, v3, v3
	v_and_b32_e32 v3, 0xffff0000, v147
	v_fmac_f32_e32 v5, v3, v3
	v_lshlrev_b32_e32 v3, 16, v148
	v_mul_f32_e32 v7, v7, v7
	v_fmac_f32_e32 v7, v3, v3
	v_lshlrev_b32_e32 v3, 16, v149
	v_fmac_f32_e32 v7, v3, v3
	v_and_b32_e32 v3, 0xffff0000, v149
	v_fmac_f32_e32 v7, v3, v3
	v_lshlrev_b32_e32 v3, 16, v150
	v_fmac_f32_e32 v7, v3, v3
	v_and_b32_e32 v3, 0xffff0000, v150
	v_fmac_f32_e32 v7, v3, v3
	v_lshlrev_b32_e32 v3, 16, v151
	v_fmac_f32_e32 v7, v3, v3
	v_and_b32_e32 v3, 0xffff0000, v151
	v_fmac_f32_e32 v7, v3, v3
	v_add_f32_e32 v3, v5, v7
	s_waitcnt vmcnt(1)
	v_and_b32_e32 v7, 0xffff0000, v152
	v_lshlrev_b32_e32 v5, 16, v152
	v_mul_f32_e32 v7, v7, v7
	v_fmac_f32_e32 v7, v5, v5
	v_lshlrev_b32_e32 v5, 16, v153
	v_fmac_f32_e32 v7, v5, v5
	v_and_b32_e32 v5, 0xffff0000, v153
	v_fmac_f32_e32 v7, v5, v5
	v_lshlrev_b32_e32 v5, 16, v154
	v_fmac_f32_e32 v7, v5, v5
	v_and_b32_e32 v5, 0xffff0000, v154
	s_cselect_b32 s17, 0xff, 63
	s_add_u32 s15, s63, s15
	v_fmac_f32_e32 v7, v5, v5
	v_lshlrev_b32_e32 v5, 16, v155
	s_addc_u32 s16, s4, s16
	s_lshl_b32 s14, s14, 8
	v_fmac_f32_e32 v7, v5, v5
	v_and_b32_e32 v5, 0xffff0000, v155
	s_add_u32 s33, s15, s14
	v_fmac_f32_e32 v7, v5, v5
	s_waitcnt vmcnt(0)
	v_and_b32_e32 v5, 0xffff0000, v156
	s_addc_u32 s37, s16, 0
	s_lshr_b32 s44, s11, 1
	s_ashr_i32 s11, s10, 31
	v_add_f32_e32 v16, v3, v7
	v_lshlrev_b32_e32 v3, 16, v156
	v_mul_f32_e32 v17, v5, v5
	s_lshl_b64 s[14:15], s[10:11], 8
	v_fmac_f32_e32 v17, v3, v3
	v_lshlrev_b32_e32 v3, 16, v157
	s_add_u32 s14, s33, s14
	v_fmac_f32_e32 v17, v3, v3
	v_and_b32_e32 v3, 0xffff0000, v157
	s_addc_u32 s15, s37, s15
	s_lshl_b32 s11, s7, 14
	v_fmac_f32_e32 v17, v3, v3
	v_lshlrev_b32_e32 v3, 16, v158
	s_add_i32 s45, s11, 0
	s_lshl_b32 s11, s5, 12
	v_fmac_f32_e32 v17, v3, v3
	s_add_i32 s45, s45, s11
	v_lshlrev_b64 v[168:169], 1, v[0:1]
	v_mov_b32_e32 v3, v1
	v_lshl_add_u64 v[8:9], s[14:15], 0, v[168:169]
	s_mov_b32 m0, s45
	v_lshlrev_b64 v[170:171], 1, v[2:3]
	v_mov_b32_e32 v5, v1
	global_load_lds_dwordx4 v[8:9], off
	v_lshl_add_u64 v[2:3], s[14:15], 0, v[170:171]
	s_add_i32 m0, s45, 0x400
	v_lshlrev_b64 v[172:173], 1, v[4:5]
	global_load_lds_dwordx4 v[2:3], off
	v_lshl_add_u64 v[2:3], s[14:15], 0, v[172:173]
	s_add_i32 m0, s45, 0x800
	v_mov_b32_e32 v7, v1
	global_load_lds_dwordx4 v[2:3], off
	v_lshlrev_b64 v[174:175], 1, v[6:7]
	s_add_i32 m0, s45, 0xc00
	v_lshl_add_u64 v[2:3], s[14:15], 0, v[174:175]
	s_add_u32 s14, s14, 0x4000
	s_addc_u32 s15, s15, 0
	global_load_lds_dwordx4 v[2:3], off
	s_add_i32 m0, s45, 0x8000
	v_lshl_add_u64 v[2:3], s[14:15], 0, v[168:169]
	global_load_lds_dwordx4 v[2:3], off
	v_lshl_add_u64 v[2:3], s[14:15], 0, v[170:171]
	s_add_i32 m0, s45, 0x8400
	v_and_b32_e32 v0, 0xffff0000, v158
	global_load_lds_dwordx4 v[2:3], off
	v_lshl_add_u64 v[2:3], s[14:15], 0, v[172:173]
	s_add_i32 m0, s45, 0x8800
	v_fmac_f32_e32 v17, v0, v0
	global_load_lds_dwordx4 v[2:3], off
	v_lshl_add_u64 v[2:3], s[14:15], 0, v[174:175]
	s_add_i32 m0, s45, 0x8c00
	v_lshlrev_b32_e32 v0, 16, v159
	global_load_lds_dwordx4 v[2:3], off
	v_fmac_f32_e32 v17, v0, v0
	v_and_b32_e32 v0, 0xffff0000, v159
	v_fmac_f32_e32 v17, v0, v0
	v_add_f32_e32 v0, v16, v17
	v_mov_b32_e32 v2, v0
	s_nop 1
	v_permlane32_swap_b32_e32 v0, v2
	v_add_f32_e32 v0, v0, v2
	v_mul_f32_e32 v2, 0x4f800000, v0
	v_cmp_gt_f32_e32 vcc, s65, v0
	v_lshlrev_b32_e32 v3, 4, v14
	v_or3_b32 v196, v3, v13, v12
	v_cndmask_b32_e32 v0, v0, v2, vcc
	v_sqrt_f32_e32 v2, v0
	s_min_i32 s11, s17, s12
	s_ashr_i32 s46, s11, 1
	s_lshl_b32 s11, s3, 2
	v_add_u32_e32 v3, -1, v2
	v_fma_f32 v4, -v3, v2, v0
	v_cmp_ge_f32_e64 s[38:39], 0, v4
	v_add_u32_e32 v4, 1, v2
	s_add_i32 s48, s11, 0
	v_cndmask_b32_e64 v3, v2, v3, s[38:39]
	v_fma_f32 v2, -v4, v2, v0
	v_cmp_lt_f32_e64 s[38:39], 0, v2
	s_or_b32 s47, s23, 31
	s_add_i32 s48, s48, 0x20440
	v_cndmask_b32_e64 v2, v3, v4, s[38:39]
	v_mul_f32_e32 v3, 0x37800000, v2
	v_cndmask_b32_e32 v2, v2, v3, vcc
	v_cmp_class_f32_e32 vcc, v0, v227
	s_add_i32 s49, s22, 1
	s_cmp_lt_i32 s22, s46
	v_cndmask_b32_e32 v0, v2, v0, vcc
	v_mul_f32_e32 v176, 0x3fb8aa3b, v15
	v_mul_f32_e32 v0, 0x3e3a82f9, v0
	s_cselect_b32 s11, s49, -1
	s_add_i32 s12, s22, -1
	s_or_b32 s50, s10, 1
	v_mov_b32_e32 v14, v1
	v_mov_b32_e32 v15, v1
	v_mul_f32_e32 v197, s13, v0
	v_sub_u32_e32 v198, v11, v10
	v_xor_b32_e32 v178, 0x80000000, v176
	s_cmp_gt_i32 s22, s44
	v_mov_b32_e32 v0, v1
	v_mov_b32_e32 v2, v1
	v_mov_b32_e32 v3, v1
	v_mov_b32_e32 v4, v1
	v_mov_b32_e32 v6, v1
	v_mov_b32_e32 v8, v1
	v_mov_b32_e32 v9, v1
	v_mov_b32_e32 v10, v1
	v_mov_b32_e32 v11, v1
	v_mov_b32_e32 v12, v1
	v_mov_b32_e32 v13, v1
	v_mov_b64_e32 v[30:31], v[14:15]
	v_mov_b64_e32 v[46:47], v[14:15]
	v_mov_b64_e32 v[62:63], v[14:15]
	v_mov_b64_e32 v[78:79], v[14:15]
	s_mov_b32 s25, 0
	v_cmp_eq_u32_e64 s[38:39], 0, v181
	s_cselect_b32 s79, s12, s11
	s_cselect_b32 s78, 1, 2
	v_mov_b32_e32 v177, v176
	v_mov_b32_e32 v179, v178
	v_mul_f32_e32 v201, 0xc27c0000, v176
	v_add_f32_e32 v201, 0x41000000, v201
	s_nop 0
	v_readfirstlane_b32 s100, v201
	v_mov_b32_e32 v201, 0
	v_mov_b32_e32 v199, 0
	s_mov_b32 s83, 0
	v_mov_b32_e32 v180, 0
	v_mov_b64_e32 v[28:29], v[12:13]
	v_mov_b64_e32 v[26:27], v[10:11]
	v_mov_b64_e32 v[24:25], v[8:9]
	v_mov_b64_e32 v[22:23], v[6:7]
	v_mov_b64_e32 v[20:21], v[4:5]
	v_mov_b64_e32 v[18:19], v[2:3]
	v_mov_b64_e32 v[16:17], v[0:1]
	v_mov_b64_e32 v[44:45], v[12:13]
	v_mov_b64_e32 v[42:43], v[10:11]
	v_mov_b64_e32 v[40:41], v[8:9]
	v_mov_b64_e32 v[38:39], v[6:7]
	v_mov_b64_e32 v[36:37], v[4:5]
	v_mov_b64_e32 v[34:35], v[2:3]
	v_mov_b64_e32 v[32:33], v[0:1]
	v_mov_b64_e32 v[60:61], v[12:13]
	v_mov_b64_e32 v[58:59], v[10:11]
	v_mov_b64_e32 v[56:57], v[8:9]
	v_mov_b64_e32 v[54:55], v[6:7]
	v_mov_b64_e32 v[52:53], v[4:5]
	v_mov_b64_e32 v[50:51], v[2:3]
	v_mov_b64_e32 v[48:49], v[0:1]
	v_mov_b64_e32 v[76:77], v[12:13]
	v_mov_b64_e32 v[74:75], v[10:11]
	v_mov_b64_e32 v[72:73], v[8:9]
	v_mov_b64_e32 v[70:71], v[6:7]
	v_mov_b64_e32 v[68:69], v[4:5]
	v_mov_b64_e32 v[66:67], v[2:3]
	v_mov_b64_e32 v[64:65], v[0:1]
	s_mov_b32 s18, s22
	s_mov_b32 s10, 0
	v_readfirstlane_b32 s101, v195
	s_cmpk_lt_u32 s101, 0x100
	s_cbranch_scc1 .Lmy_prio_lo
	s_setprio 1
